# baseline (speedup 1.0000x reference)
; __device__ __forceinline__ int tid_() { int t = threadIdx.x; asm volatile("" : "+v"(t)); return t; }
; __device__ __forceinline__ void phase_final(float* x, const float* g, int bid, int nb) {
;   const int tidn = tid_();
;   int wid = tidn >> 6, lane = tidn & 63;
;   for (int r = bid * 8 + wid; r < T_ALL; r += nb * 8) {
;     float* xr = x + (long)r * D;
;     float4 v[4];
;     float ss = 0.f;
; #pragma unroll
;     for (int i = 0; i < 4; ++i) {
;       v[i] = *(const float4*)(xr + i * 256 + lane * 4);
;       ss += v[i].x * v[i].x + v[i].y * v[i].y + v[i].z * v[i].z + v[i].w * v[i].w;
;     }
; #pragma unroll
;     for (int o = 32; o >= 1; o >>= 1) ss += shfl_xor_l(ss, lane, o);
;     float rinv = rsqrtf(ss * (1.0f / D) + EPS);
; #pragma unroll
;     for (int i = 0; i < 4; ++i) {
;       float4 gg = *(const float4*)(g + i * 256 + lane * 4);
;       float4 o = make_float4(v[i].x * rinv * gg.x, v[i].y * rinv * gg.y, v[i].z * rinv * gg.z, v[i].w * rinv * gg.w);
;       *(float4*)(xr + i * 256 + lane * 4) = o;
;     }
;   }
; }
.LBB0_13:
	global_load_dwordx4 v[12:15], v[4:5], off
	global_load_dwordx4 v[16:19], v[2:3], off
	global_load_dwordx4 v[20:23], v[4:5], off offset:1024
	global_load_dwordx4 v[208:211], v[4:5], off offset:2048
	global_load_dwordx4 v[212:215], v[4:5], off offset:3072
	global_load_dwordx4 v[196:199], v[2:3], off offset:1024
	global_load_dwordx4 v[200:203], v[2:3], off offset:2048
	global_load_dwordx4 v[204:207], v[2:3], off offset:3072
	v_add_u32_e32 v6, s62, v6
	s_mov_b32 s10, 0x13fff
	s_waitcnt vmcnt(0)
	v_mov_b32_e32 v26, v13
	v_mov_b32_e32 v24, v12
	s_waitcnt vmcnt(0)
	v_mov_b32_e32 v27, v21
	v_mov_b32_e32 v25, v20
	v_pk_mul_f32 v[26:27], v[26:27], v[26:27]
	v_mov_b32_e32 v28, v15
	v_pk_fma_f32 v[24:25], v[24:25], v[24:25], v[26:27]
	v_mov_b32_e32 v26, v14
	v_mov_b32_e32 v27, v22
	v_mov_b32_e32 v29, v23
	v_pk_fma_f32 v[24:25], v[26:27], v[26:27], v[24:25]
	s_nop 0
	v_pk_fma_f32 v[32:33], v[28:29], v[28:29], v[24:25]
	v_mov_b64_e32 v[24:25], v[208:209]
	v_mov_b64_e32 v[26:27], v[210:211]
	v_mov_b64_e32 v[28:29], v[212:213]
	v_mov_b64_e32 v[30:31], v[214:215]
	v_add_f32_e32 v32, v32, v33
	s_waitcnt vmcnt(1)
	v_mov_b32_e32 v36, v25
	s_waitcnt vmcnt(0)
	v_mov_b32_e32 v37, v29
	v_mov_b32_e32 v34, v24
	v_mov_b32_e32 v35, v28
	v_pk_mul_f32 v[36:37], v[36:37], v[36:37]
	v_mov_b32_e32 v38, v27
	v_pk_fma_f32 v[34:35], v[34:35], v[34:35], v[36:37]
	v_mov_b32_e32 v36, v26
	v_mov_b32_e32 v37, v30
	v_mov_b32_e32 v39, v31
	v_pk_fma_f32 v[34:35], v[36:37], v[36:37], v[34:35]
	s_nop 0
	v_pk_fma_f32 v[34:35], v[38:39], v[38:39], v[34:35]
	s_nop 0
	v_add_f32_e32 v32, v32, v34
	v_add_f32_e32 v32, v32, v35
	ds_bpermute_b32 v33, v0, v32
	s_waitcnt lgkmcnt(0)
	v_add_f32_e32 v32, v32, v33
	ds_bpermute_b32 v33, v7, v32
	s_waitcnt lgkmcnt(0)
	v_add_f32_e32 v32, v32, v33
	s_nop 1
	v_add_f32_dpp v32, v32, v32 quad_perm:[1,0,3,2] row_mask:0xf bank_mask:0xf
	s_nop 1
	v_add_f32_dpp v32, v32, v32 quad_perm:[2,3,0,1] row_mask:0xf bank_mask:0xf
	s_nop 1
	v_add_f32_dpp v32, v32, v32 row_half_mirror row_mask:0xf bank_mask:0xf
	s_nop 1
	v_add_f32_dpp v32, v32, v32 row_mirror row_mask:0xf bank_mask:0xf
	v_fmamk_f32 v32, v32, 0x3a800000, v183
	v_cmp_gt_f32_e32 vcc, s18, v32
	v_mul_f32_e32 v33, 0x4b800000, v32
	s_nop 0
	v_cndmask_b32_e32 v32, v32, v33, vcc
	v_rsq_f32_e32 v32, v32
	s_nop 0
	v_mul_f32_e32 v33, 0x45800000, v32
	v_cndmask_b32_e32 v32, v32, v33, vcc
	v_pk_mul_f32 v[12:13], v[12:13], v[32:33] op_sel_hi:[1,0]
	v_pk_mul_f32 v[14:15], v[14:15], v[32:33] op_sel_hi:[1,0]
	v_pk_mul_f32 v[12:13], v[16:17], v[12:13]
	v_pk_mul_f32 v[14:15], v[18:19], v[14:15]
	global_store_dwordx4 v[4:5], v[12:15], off
	s_nop 1
	v_mov_b64_e32 v[12:13], v[196:197]
	v_mov_b64_e32 v[14:15], v[198:199]
	v_pk_mul_f32 v[16:17], v[20:21], v[32:33] op_sel_hi:[1,0]
	v_cmp_lt_i32_e32 vcc, s10, v6
	s_or_b64 s[8:9], vcc, s[8:9]
	s_nop 0
	v_pk_mul_f32 v[12:13], v[12:13], v[16:17]
	v_pk_mul_f32 v[16:17], v[22:23], v[32:33] op_sel_hi:[1,0]
	s_nop 0
	v_pk_mul_f32 v[14:15], v[14:15], v[16:17]
	global_store_dwordx4 v[4:5], v[12:15], off offset:1024
	s_nop 1
	v_mov_b64_e32 v[12:13], v[200:201]
	v_mov_b64_e32 v[14:15], v[202:203]
	v_pk_mul_f32 v[16:17], v[24:25], v[32:33] op_sel_hi:[1,0]
	s_nop 0
	v_pk_mul_f32 v[12:13], v[16:17], v[12:13]
	v_pk_mul_f32 v[16:17], v[26:27], v[32:33] op_sel_hi:[1,0]
	s_nop 0
	v_pk_mul_f32 v[14:15], v[16:17], v[14:15]
	global_store_dwordx4 v[4:5], v[12:15], off offset:2048
	s_nop 1
	v_mov_b64_e32 v[12:13], v[204:205]
	v_mov_b64_e32 v[14:15], v[206:207]
	v_pk_mul_f32 v[16:17], v[28:29], v[32:33] op_sel_hi:[1,0]
	s_nop 0
	v_pk_mul_f32 v[12:13], v[16:17], v[12:13]
	v_pk_mul_f32 v[16:17], v[30:31], v[32:33] op_sel_hi:[1,0]
	s_nop 0
	v_pk_mul_f32 v[14:15], v[16:17], v[14:15]
	global_store_dwordx4 v[4:5], v[12:15], off offset:3072
	v_lshl_add_u64 v[4:5], v[4:5], 0, s[16:17]
	s_andn2_b64 exec, exec, s[8:9]
	s_cbranch_execnz .LBB0_13

; __device__ __forceinline__ void run_phase(const Params& P, char* shm, int ph, int bid, int nb) {
;   if (ph == 0) { phase_prep(P, shm, bid, nb); return; }
;   if (ph == N_PHASES - 1) { phase_final(P.x, P.final_g, bid, nb); return; }
;   int q = ph - 1;
;   int grp = q / PH_PER_GRP;
;   int qq = q % PH_PER_GRP;
;   float* xg = P.x + (long)P.gtok0 * D;
;   const int nM = P.tg / 256;
;   if (qq == 0) { phase_x0(P, P.gtok0, xg, P.xn, P.sq1, P.tg, bid, nb); return; }
;   int l = (qq - 1) / PH_PER_LAYER;
;   int s = (qq - 1) % PH_PER_LAYER;
;   switch (s) {
; template <bool COOP>
; __global__ void __launch_bounds__(NTHR) mega(KArgs K, int ph_lo, int ph_hi) {
;     ...
;       const int grp = (ph - 1) / PH_PER_GRP;
;       P.tg = grp <= 0 ? TG0 : TG1;
;       P.gtok0 = grp <= 0 ? 0 : TG0;
.LBB0_17:
	s_cmp_lt_i32 s42, 34
	s_mov_b32 s4, 0xc000
	s_cselect_b32 s93, s4, 0x8000
	s_cselect_b32 s75, 0, 0xc000
	s_add_i32 s4, s42, -1
	s_mul_hi_i32 s5, s4, 0x3e0f83e1
	s_lshr_b32 s6, s5, 31
	s_ashr_i32 s5, s5, 3
	s_add_i32 s5, s5, s6
	s_mul_i32 s5, s5, 33
	s_sub_i32 s27, s4, s5
	s_lshl_b32 s4, s75, 12
	s_mov_b32 s5, s59
	s_cmp_lg_u32 s27, 0
	v_writelane_b32 v249, s4, 56
	s_nop 1
	v_writelane_b32 v249, s5, 57
	s_cbranch_scc0 .LBB0_53
	s_add_i32 s4, s27, -1
	s_bfe_i32 s5, s4, 0x80000
	s_bfe_u32 s5, s5, 0x3000c
	s_add_i32 s5, s4, s5
	s_bfe_i32 s6, s5, 0x80000
	s_sext_i32_i16 s6, s6
	s_and_b32 s5, s5, 0xf8
	s_lshr_b32 s45, s6, 3
	s_ashr_i32 s6, s6, 3
	s_sub_i32 s4, s4, s5
	v_writelane_b32 v249, s6, 58
	s_and_b32 s28, s4, 0xff
	s_lshr_b32 s4, s93, 8
	v_writelane_b32 v249, s4, 59
	s_add_u32 s4, s2, 0x8400800
	s_addc_u32 s5, s3, 0
	s_add_u32 s54, s2, 0x30e00000
	s_addc_u32 s55, s3, 0
	s_add_u32 s12, s2, 0x3ce00000
	v_writelane_b32 v249, s4, 60
	s_addc_u32 s13, s3, 0
	v_writelane_b32 v248, s54, 0
	v_writelane_b32 v249, s5, 61
	s_add_u32 s4, s2, 0x4dc04040
	v_writelane_b32 v249, s4, 62
	s_addc_u32 s4, s3, 0
	v_writelane_b32 v249, s4, 63
	s_cmp_lt_i32 s28, 4
	s_mov_b64 s[4:5], -1
	v_writelane_b32 v248, s55, 1
	s_cbranch_scc1 .LBB0_150
	v_readlane_b32 s4, v250, 0
	v_readlane_b32 s6, v250, 2
	v_readlane_b32 s7, v250, 3
	v_readlane_b32 s6, v249, 56
	v_readlane_b32 s5, v250, 1
	v_readlane_b32 s7, v249, 57
	s_add_u32 s6, s4, s6
	s_addc_u32 s7, s5, 0
	s_add_u32 s29, s2, 0x4df14040
	s_addc_u32 s30, s3, 0
	s_and_b32 s31, 0xffff, s28
	s_cmp_lt_i32 s31, 6
	s_mov_b64 s[4:5], -1
	s_cbranch_scc1 .LBB0_85
	s_cmp_lt_i32 s31, 7
	s_cbranch_scc1 .LBB0_55
	s_cmp_eq_u32 s31, 7
	s_cbranch_scc0 .LBB0_54
	s_lshr_b32 s16, s93, 6
	v_readlane_b32 s4, v249, 1
	s_cmp_ge_i32 s4, s16
	s_cbranch_scc1 .LBB0_54
	v_readlane_b32 s4, v249, 58
	s_mul_i32 s4, s4, 0x2c0000
	s_ashr_i32 s5, s4, 31
	s_lshl_b64 s[4:5], s[4:5], 1
	v_readlane_b32 s8, v249, 52
	v_readlane_b32 s9, v249, 53
	s_add_u32 s17, s8, s4
	s_addc_u32 s18, s9, s5
	s_add_u32 s19, s2, s4
	s_addc_u32 s20, s3, s5
	s_mov_b64 s[8:9], 0
	v_readlane_b32 s21, v249, 1
	s_branch .LBB0_25
	s_nop 0
	s_nop 0
	s_nop 0
	s_nop 0
	s_nop 0
	s_nop 0
	s_nop 0
	s_nop 0
	s_nop 0
	s_nop 0
	s_nop 0
	s_nop 0
	s_nop 0
	s_nop 0
	s_nop 0
	s_nop 0
	s_nop 0
	s_nop 0
	s_nop 0
	s_nop 0
	s_nop 0
	s_nop 0
	s_nop 0
	s_nop 0
	s_nop 0
	s_nop 0
	s_nop 0
	s_nop 0
	s_nop 0
	s_nop 0
	s_nop 0
	s_nop 0
	s_nop 0
	s_nop 0
	s_nop 0
	s_nop 0
	s_nop 0
	s_nop 0
	s_nop 0
	s_nop 0
	s_nop 0
	s_nop 0
	s_nop 0
	s_nop 0
	s_nop 0
	s_nop 0
	s_nop 0
	s_nop 0
	s_nop 0
	s_nop 0
	s_nop 0
	s_nop 0
	s_nop 0
	s_nop 0
	s_nop 0

; __device__ __forceinline__ float bf2f(u16 h) { return __uint_as_float(((unsigned)h) << 16); }
; __device__ __forceinline__ void phase_ain(const Params& P, int l, int bid, int nb) {
;     ...
;   for (int r = bid * 8 + wid; r < P.tg; r += nb * 8) {
;     float ov[16];
;     float ss = 0.f;
; #pragma unroll
;     for (int hh = 0; hh < 2; ++hh) {
;       u16x8 a = *(const u16x8*)(P.of + (long)r * D + c0 + hh * 8);
;       u16x8 a2 = *(const u16x8*)(P.h + (long)r * HS + c0 + hh * 8);
;       u16x8 b2 = *(const u16x8*)(P.h + (long)r * HS + 1024 + c0 + hh * 8);
; #pragma unroll
;       for (int e = 0; e < 8; ++e) { float v = bf2f(a[e]) + (bf2f(a2[e]) + bf2f(b2[e])); ov[hh * 8 + e] = v; ss += v * v; }
.LBB0_155:
	v_lshl_add_u64 v[30:31], v[20:21], 0, v[0:1]
	v_add_co_u32_e32 v6, vcc, 0x30e00000, v30
	v_lshl_add_u64 v[34:35], v[22:23], 0, v[0:1]
	s_nop 0
	v_addc_co_u32_e32 v7, vcc, 0, v31, vcc
	v_add_co_u32_e32 v8, vcc, 0xe600000, v34
	global_load_dwordx4 v[2:5], v[6:7], off
	s_nop 0
	v_addc_co_u32_e32 v9, vcc, 0, v35, vcc
	global_load_dwordx4 v[26:29], v[8:9], off
	global_load_dwordx4 v[42:45], v[8:9], off offset:2048
	global_load_dwordx4 v[14:17], v[6:7], off offset:16
	global_load_dwordx4 v[10:13], v[8:9], off offset:16
	s_nop 0
	global_load_dwordx4 v[6:9], v[8:9], off offset:2064
	s_mov_b32 s8, 0xe601000
	v_add_co_u32_e32 v58, vcc, s8, v34
	v_add_u32_e32 v36, s62, v36
	s_nop 0
	v_addc_co_u32_e32 v59, vcc, 0, v35, vcc
	v_lshl_add_u64 v[20:21], v[20:21], 0, s[10:11]
	v_lshl_add_u64 v[22:23], v[22:23], 0, s[14:15]
	global_load_dwordx4 v[196:199], v[58:59], off
	global_load_dwordx4 v[200:203], v[18:19], off offset:16
	global_load_dwordx4 v[204:207], v[18:19], off
	global_load_dwordx4 v[208:211], v[58:59], off offset:16
	global_load_dwordx4 v[212:215], v[18:19], off offset:48
	global_load_dwordx4 v[216:219], v[18:19], off offset:32
	s_waitcnt vmcnt(0) lgkmcnt(0)
	v_and_b32_e32 v51, 0xffff0000, v26
	v_and_b32_e32 v35, 0xffff0000, v2
	v_lshlrev_b32_e32 v34, 16, v2
	v_and_b32_e32 v33, 0xffff0000, v13
	v_lshlrev_b32_e32 v32, 16, v13
	v_and_b32_e32 v47, 0xffff0000, v9
	v_lshlrev_b32_e32 v46, 16, v9
	v_pk_add_f32 v[32:33], v[32:33], v[46:47]
	v_mov_b64_e32 v[46:47], v[196:197]
	v_mov_b64_e32 v[48:49], v[198:199]
	v_lshlrev_b32_e32 v50, 16, v26
	v_lshlrev_b32_e32 v26, 16, v43
	v_and_b32_e32 v53, 0xffff0000, v42
	v_lshlrev_b32_e32 v52, 16, v42
	v_and_b32_e32 v67, 0xffff0000, v44
	v_lshlrev_b32_e32 v66, 16, v44
	v_pk_add_f32 v[50:51], v[50:51], v[52:53]
	v_and_b32_e32 v13, 0xffff0000, v12
	v_pk_add_f32 v[34:35], v[50:51], v[34:35]
	v_mov_b64_e32 v[50:51], v[200:201]
	v_mov_b64_e32 v[52:53], v[202:203]
	v_mov_b64_e32 v[54:55], v[204:205]
	v_mov_b64_e32 v[56:57], v[206:207]
	v_lshlrev_b32_e32 v12, 16, v12
	v_pk_mul_f32 v[60:61], v[34:35], v[34:35]
	v_and_b32_e32 v25, 0xffff0000, v17
	v_lshlrev_b32_e32 v24, 16, v17
	v_pk_add_f32 v[24:25], v[32:33], v[24:25]
	s_waitcnt vmcnt(0) lgkmcnt(0)
	v_lshlrev_b32_e32 v62, 16, v46
	v_mul_f32_e32 v2, 0xbfb8aa3b, v62
	v_exp_f32_e32 v2, v2
	v_and_b32_e32 v63, 0xffff0000, v46
	v_pk_mul_f32 v[32:33], v[24:25], v[24:25]
	v_add_f32_e32 v2, 1.0, v2
	v_rcp_f32_e32 v64, v2
	v_mul_f32_e32 v2, 0xbfb8aa3b, v63
	v_exp_f32_e32 v2, v2
	s_nop 0
	v_add_f32_e32 v2, 1.0, v2
	v_rcp_f32_e32 v65, v2
	v_lshlrev_b32_e32 v2, 16, v27
	v_pk_mul_f32 v[62:63], v[64:65], v[62:63]
	v_and_b32_e32 v65, 0xffff0000, v3
	v_lshlrev_b32_e32 v64, 16, v3
	v_and_b32_e32 v3, 0xffff0000, v27
	v_and_b32_e32 v27, 0xffff0000, v43
	v_pk_add_f32 v[2:3], v[2:3], v[26:27]
	s_nop 0
	v_pk_add_f32 v[42:43], v[2:3], v[64:65]
	v_lshlrev_b32_e32 v2, 16, v47
	v_mul_f32_e32 v9, 0xbfb8aa3b, v2
	v_exp_f32_e32 v9, v9
	v_and_b32_e32 v3, 0xffff0000, v47
	v_pk_mul_f32 v[64:65], v[42:43], v[42:43]
	v_add_f32_e32 v9, 1.0, v9
	v_rcp_f32_e32 v26, v9
	v_mul_f32_e32 v9, 0xbfb8aa3b, v3
	v_exp_f32_e32 v9, v9
	s_nop 0
	v_add_f32_e32 v9, 1.0, v9
	v_rcp_f32_e32 v27, v9
	v_and_b32_e32 v9, 0xffff0000, v8
	v_lshlrev_b32_e32 v8, 16, v8
	v_pk_add_f32 v[8:9], v[12:13], v[8:9]
	v_pk_mul_f32 v[46:47], v[26:27], v[2:3]
	v_and_b32_e32 v27, 0xffff0000, v28
	v_lshlrev_b32_e32 v26, 16, v28
	v_and_b32_e32 v3, 0xffff0000, v4
	v_lshlrev_b32_e32 v2, 16, v4
	v_pk_add_f32 v[26:27], v[26:27], v[66:67]
	v_lshlrev_b32_e32 v28, 16, v10
	v_pk_add_f32 v[66:67], v[26:27], v[2:3]
	v_lshlrev_b32_e32 v2, 16, v48
	v_mul_f32_e32 v4, 0xbfb8aa3b, v2
	v_exp_f32_e32 v4, v4
	v_and_b32_e32 v3, 0xffff0000, v48
	v_pk_mul_f32 v[68:69], v[66:67], v[66:67]
	v_add_f32_e32 v4, 1.0, v4
	v_rcp_f32_e32 v26, v4
	v_mul_f32_e32 v4, 0xbfb8aa3b, v3
	v_exp_f32_e32 v4, v4
	s_nop 0
	v_add_f32_e32 v4, 1.0, v4
	v_rcp_f32_e32 v27, v4
	v_lshlrev_b32_e32 v4, 16, v29
	v_pk_mul_f32 v[70:71], v[26:27], v[2:3]
	v_and_b32_e32 v3, 0xffff0000, v5
	v_lshlrev_b32_e32 v2, 16, v5
	v_and_b32_e32 v5, 0xffff0000, v29
	v_and_b32_e32 v27, 0xffff0000, v45
	v_lshlrev_b32_e32 v26, 16, v45
	v_pk_add_f32 v[4:5], v[4:5], v[26:27]
	v_and_b32_e32 v29, 0xffff0000, v10
	v_pk_add_f32 v[44:45], v[4:5], v[2:3]
	v_and_b32_e32 v3, 0xffff0000, v49
	v_lshlrev_b32_e32 v2, 16, v49
	v_mul_f32_e32 v4, 0xbfb8aa3b, v2
	v_mul_f32_e32 v5, 0xbfb8aa3b, v3
	v_exp_f32_e32 v4, v4
	v_exp_f32_e32 v5, v5
	v_and_b32_e32 v27, 0xffff0000, v14
	v_lshlrev_b32_e32 v26, 16, v14
	v_add_f32_e32 v4, 1.0, v4
	v_add_f32_e32 v5, 1.0, v5
	v_rcp_f32_e32 v4, v4
	v_rcp_f32_e32 v5, v5
	v_lshlrev_b32_e32 v14, 16, v11
	v_lshlrev_b32_e32 v10, 16, v7
	v_pk_mul_f32 v[72:73], v[44:45], v[44:45]
	v_pk_mul_f32 v[48:49], v[4:5], v[2:3]
	v_mov_b64_e32 v[2:3], v[208:209]
	v_mov_b64_e32 v[4:5], v[210:211]
	v_and_b32_e32 v59, 0xffff0000, v6
	v_lshlrev_b32_e32 v58, 16, v6
	v_pk_add_f32 v[28:29], v[28:29], v[58:59]
	s_nop 0
	v_pk_add_f32 v[26:27], v[28:29], v[26:27]
	s_waitcnt vmcnt(0) lgkmcnt(0)
; __device__ __forceinline__ float bf2f(u16 h) { return __uint_as_float(((unsigned)h) << 16); }
; __device__ __forceinline__ float siluf_(float x) { return x * __builtin_amdgcn_rcpf(1.0f + __expf(-x)); }
; __device__ __forceinline__ void phase_ain(const Params& P, int l, int bid, int nb) {
;     ...
;       for (int e = 0; e < 8; ++e) { float v = bf2f(a[e]) + (bf2f(a2[e]) + bf2f(b2[e])); ov[hh * 8 + e] = v; ss += v * v; }
;     }
; #pragma unroll
;     for (int o = 8; o >= 1; o >>= 1) ss += shfl_xor_l(ss, lane, o);
;     float rinv = rsqrtf(ss * (1.0f / 256.0f) + EPS);
; #pragma unroll
;     for (int hh = 0; hh < 2; ++hh) {
;       u16x8 rv = *(const u16x8*)(P.h + (long)r * HS + C_R + c0 + hh * 8);
;       u16x8 o;
; #pragma unroll
;       for (int e = 0; e < 8; ++e) o[e] = f2bf(ov[hh * 8 + e] * rinv * og[c0 + hh * 8 + e] * siluf_(bf2f(rv[e])));
;       *(u16x8*)(P.ain + (long)r * D + c0 + hh * 8) = o;
;     }
	v_lshlrev_b32_e32 v28, 16, v2
	v_and_b32_e32 v29, 0xffff0000, v2
	v_mul_f32_e32 v2, 0xbfb8aa3b, v28
	v_exp_f32_e32 v2, v2
	v_pk_mul_f32 v[58:59], v[26:27], v[26:27]
	v_add_f32_e32 v2, 1.0, v2
	v_rcp_f32_e32 v74, v2
	v_mul_f32_e32 v2, 0xbfb8aa3b, v29
	v_exp_f32_e32 v2, v2
	s_nop 0
	v_add_f32_e32 v2, 1.0, v2
	v_rcp_f32_e32 v75, v2
	s_nop 0
	v_pk_mul_f32 v[28:29], v[74:75], v[28:29]
	v_and_b32_e32 v75, 0xffff0000, v15
	v_lshlrev_b32_e32 v74, 16, v15
	v_and_b32_e32 v15, 0xffff0000, v11
	v_and_b32_e32 v11, 0xffff0000, v7
	v_pk_add_f32 v[6:7], v[14:15], v[10:11]
	v_and_b32_e32 v15, 0xffff0000, v3
	v_lshlrev_b32_e32 v14, 16, v3
	v_mul_f32_e32 v2, 0xbfb8aa3b, v14
	v_mul_f32_e32 v3, 0xbfb8aa3b, v15
	v_exp_f32_e32 v2, v2
	v_exp_f32_e32 v3, v3
	v_pk_add_f32 v[10:11], v[6:7], v[74:75]
	v_add_f32_e32 v2, 1.0, v2
	v_add_f32_e32 v3, 1.0, v3
	v_rcp_f32_e32 v2, v2
	v_rcp_f32_e32 v3, v3
	v_pk_mul_f32 v[6:7], v[10:11], v[10:11]
	v_pk_mul_f32 v[2:3], v[2:3], v[14:15]
	v_and_b32_e32 v15, 0xffff0000, v16
	v_lshlrev_b32_e32 v14, 16, v16
	v_pk_add_f32 v[12:13], v[8:9], v[14:15]
	v_add_f32_e32 v14, v60, v61
	v_add_f32_e32 v14, v64, v14
	v_add_f32_e32 v14, v65, v14
	v_add_f32_e32 v14, v68, v14
	v_add_f32_e32 v14, v69, v14
	v_add_f32_e32 v14, v72, v14
	v_add_f32_e32 v14, v73, v14
	v_add_f32_e32 v14, v58, v14
	v_add_f32_e32 v14, v59, v14
	v_add_f32_e32 v6, v6, v14
	v_pk_mul_f32 v[8:9], v[12:13], v[12:13]
	v_add_f32_e32 v6, v7, v6
	v_add_f32_e32 v6, v8, v6
	v_add_f32_e32 v6, v9, v6
	v_add_f32_e32 v6, v32, v6
	v_add_f32_e32 v6, v33, v6
	s_nop 1
	v_add_f32_dpp v6, v6, v6 quad_perm:[1,0,3,2] row_mask:0xf bank_mask:0xf
	s_nop 1
	v_add_f32_dpp v6, v6, v6 quad_perm:[2,3,0,1] row_mask:0xf bank_mask:0xf
	s_nop 1
	v_add_f32_dpp v6, v6, v6 row_half_mirror row_mask:0xf bank_mask:0xf
	s_nop 1
	v_add_f32_dpp v6, v6, v6 row_mirror row_mask:0xf bank_mask:0xf
	v_fmamk_f32 v6, v6, 0x3b800000, v183
	v_cmp_gt_f32_e32 vcc, s9, v6
	v_mul_f32_e32 v7, 0x4b800000, v6
	s_nop 0
	v_cndmask_b32_e32 v6, v6, v7, vcc
	v_rsq_f32_e32 v6, v6
	s_nop 0
	v_mul_f32_e32 v7, 0x45800000, v6
	v_cndmask_b32_e32 v14, v6, v7, vcc
	v_pk_mul_f32 v[6:7], v[34:35], v[14:15] op_sel_hi:[1,0]
	v_pk_mul_f32 v[8:9], v[42:43], v[14:15] op_sel_hi:[1,0]
	v_pk_mul_f32 v[6:7], v[54:55], v[6:7]
	v_pk_mul_f32 v[8:9], v[56:57], v[8:9]
	v_pk_mul_f32 v[6:7], v[62:63], v[6:7]
	v_pk_mul_f32 v[8:9], v[46:47], v[8:9]
	v_cvt_pk_bf16_f32 v6, v6, v7
	v_cvt_pk_bf16_f32 v7, v8, v9
	v_pk_mul_f32 v[8:9], v[66:67], v[14:15] op_sel_hi:[1,0]
	v_pk_mul_f32 v[16:17], v[44:45], v[14:15] op_sel_hi:[1,0]
	v_pk_mul_f32 v[8:9], v[50:51], v[8:9]
	v_pk_mul_f32 v[16:17], v[52:53], v[16:17]
	v_pk_mul_f32 v[8:9], v[70:71], v[8:9]
	v_pk_mul_f32 v[16:17], v[48:49], v[16:17]
	v_cvt_pk_bf16_f32 v8, v8, v9
	v_cvt_pk_bf16_f32 v9, v16, v17
	v_add_co_u32_e32 v16, vcc, s16, v30
	v_pk_mul_f32 v[26:27], v[26:27], v[14:15] op_sel_hi:[1,0]
	s_nop 0
	v_addc_co_u32_e32 v17, vcc, 0, v31, vcc
	global_store_dwordx4 v[16:17], v[6:9], off offset:2048
	s_nop 1
	v_mov_b64_e32 v[6:7], v[212:213]
	v_mov_b64_e32 v[8:9], v[214:215]
	s_nop 0
	v_mov_b64_e32 v[30:31], v[216:217]
	v_mov_b64_e32 v[32:33], v[218:219]
	v_pk_mul_f32 v[10:11], v[10:11], v[14:15] op_sel_hi:[1,0]
	v_pk_mul_f32 v[12:13], v[12:13], v[14:15] op_sel_hi:[1,0]
	v_cmp_le_i32_e32 vcc, s93, v36
	s_or_b64 s[6:7], vcc, s[6:7]
	s_nop 0
	v_pk_mul_f32 v[6:7], v[6:7], v[12:13]
	v_pk_mul_f32 v[26:27], v[30:31], v[26:27]
	v_pk_mul_f32 v[10:11], v[32:33], v[10:11]
	v_pk_mul_f32 v[26:27], v[28:29], v[26:27]
	v_pk_mul_f32 v[2:3], v[2:3], v[10:11]
	v_cvt_pk_bf16_f32 v26, v26, v27
	v_cvt_pk_bf16_f32 v27, v2, v3
	v_lshlrev_b32_e32 v2, 16, v4
	v_and_b32_e32 v3, 0xffff0000, v4
	v_mul_f32_e32 v4, 0xbfb8aa3b, v2
	v_exp_f32_e32 v4, v4
	s_nop 0
	v_add_f32_e32 v4, 1.0, v4
	v_rcp_f32_e32 v10, v4
	v_mul_f32_e32 v4, 0xbfb8aa3b, v3
	v_exp_f32_e32 v4, v4
	s_nop 0
	v_add_f32_e32 v4, 1.0, v4
	v_rcp_f32_e32 v11, v4
	s_nop 0
	v_pk_mul_f32 v[2:3], v[10:11], v[2:3]
	s_nop 0
	v_pk_mul_f32 v[2:3], v[2:3], v[6:7]
	v_pk_mul_f32 v[6:7], v[24:25], v[14:15] op_sel_hi:[1,0]
	v_cvt_pk_bf16_f32 v28, v2, v3
	v_and_b32_e32 v3, 0xffff0000, v5
	v_lshlrev_b32_e32 v2, 16, v5
	v_mul_f32_e32 v4, 0xbfb8aa3b, v2
	v_mul_f32_e32 v5, 0xbfb8aa3b, v3
	v_exp_f32_e32 v4, v4
	v_exp_f32_e32 v5, v5
	v_pk_mul_f32 v[6:7], v[8:9], v[6:7]
	v_add_f32_e32 v4, 1.0, v4
	v_add_f32_e32 v5, 1.0, v5
	v_rcp_f32_e32 v4, v4
	v_rcp_f32_e32 v5, v5
	s_nop 0
	v_pk_mul_f32 v[2:3], v[4:5], v[2:3]
	s_nop 0
	v_pk_mul_f32 v[2:3], v[2:3], v[6:7]
	s_nop 0
	v_cvt_pk_bf16_f32 v29, v2, v3
	global_store_dwordx4 v[16:17], v[26:29], off offset:2064
	s_andn2_b64 exec, exec, s[6:7]
	s_cbranch_execnz .LBB0_155

; __device__ __forceinline__ void phase_glay_pool(const Params& P, char* shm, int grp, int l, int bid, int nb) {
;   const int gtok0 = P.gtok0, tg = P.tg;
;   const int ngla = grp == 0 ? 64 + 4 * 32 : 4 * 32;
;   const int npool = tg / 128;
;   for (int u = bid; u < ngla; u += nb) {
;     if (grp == 0 && u < 64) {
.LBB0_157:
	s_andn2_b64 vcc, exec, s[4:5]
	s_cbranch_vccnz .LBB0_303
	v_readlane_b32 s4, v248, 2
	s_add_i32 s4, s4, 31
	s_cmpk_lt_u32 s4, 0x41
	s_cselect_b64 s[14:15], -1, 0
	s_and_b64 s[4:5], s[14:15], exec
	s_movk_i32 s4, 0xc0
	s_cselect_b32 s29, s4, 0x80
	s_cmp_ge_i32 s44, s29
	s_cselect_b64 s[16:17], -1, 0
	s_and_b64 vcc, exec, s[16:17]
	s_cbranch_vccnz .LBB0_242
	s_and_b64 s[4:5], s[14:15], exec
	s_cselect_b32 s30, 0x4000, 0
	s_mov_b32 s31, s44
	s_branch .LBB0_162
	s_nop 0
	s_nop 0
	s_nop 0
	s_nop 0
	s_nop 0
	s_nop 0
	s_nop 0
	s_nop 0
	s_nop 0
	s_nop 0
	s_nop 0
	s_nop 0
	s_nop 0
	s_nop 0
	s_nop 0
	s_nop 0
	s_nop 0
	s_nop 0
	s_nop 0
	s_nop 0
	s_nop 0
	s_nop 0
	s_nop 0
	s_nop 0
	s_nop 0
	s_nop 0
	s_nop 0
	s_nop 0
	s_nop 0
	s_nop 0
	s_nop 0
	s_nop 0
	s_nop 0
	s_nop 0
	s_nop 0
	s_nop 0
	s_nop 0
	s_nop 0
	s_nop 0
	s_nop 0
	s_nop 0
	s_nop 0
	s_nop 0
	s_nop 0
	s_nop 0
	s_nop 0
	s_nop 0
	s_nop 0
	s_nop 0
	s_nop 0
	s_nop 0
	s_nop 0
	s_nop 0
	s_nop 0
	s_nop 0
